# GEMM mainloops: per-segment s_setprio flips removed; one static s_setprio 1 for the trailing half (waves 4-7) during GEMM phases
# baseline (speedup 1.0000x reference)
; #define PG8_STAGE(bufoff, gbase, voff) do { _Pragma("unroll") for (int _i = 0; _i < 2; ++_i) \
;         __builtin_amdgcn_global_load_lds((const unsigned*)((const char*)(gbase) + (voff)[_i]), (PG8_LAS unsigned*)(lds + (bufoff) + ldsw + _i * 8192), 16, 0, 0); } while (0)
; #define PG8_BAR __builtin_amdgcn_s_barrier()
; template <class Epi, class Sched, bool ALIGN_EPI = false, bool SP2 = false>
; __device__ __forceinline__ void gemm_phase(PG8_LAS unsigned char* lds, const Gemm g, const Sched& S, const Epi& E) {
;     ...
;     const int tid = tid_, wid = __builtin_amdgcn_readfirstlane(tid >> 6), lane = tid & 63, wr = wid >> 2, wc = wid & 3, fr = lane & 15, fq = lane >> 4;
;     const int K = g.K, nt = K / BK;
;     unsigned voffA[2], voffB[2];
; #pragma unroll
;     for (int i = 0; i < 2; ++i) { int R, C; stage_rc(tid * 16 + i * 8192, R, C); const int Rb = Epi::PERM ? ((R & ~31) + perm32(R & 31)) : R;
;         voffA[i] = (unsigned)(R * K + C) * 2u; voffB[i] = (unsigned)(Rb * K + C) * 2u; }
;     ...
;     const char* cA = (const char*)g.A + (size_t)cur.pm * tstep; const char* cB = (const char*)g.Bt + (size_t)cur.pn * tstep;
;     S.a_ready(cur);
;     if constexpr (SP2) {
;         PG8_STAGE(PG8_SB(0, 0), cB, voffB); PG8_STAGE(PG8_SB(0, 1), cB + hstep, voffB); PG8_STAGE(PG8_SA(0, 0), cA, voffA); PG8_STAGE(PG8_SA(0, 1), cA + hstep, voffA);
;         if (wr == 1) PG8_BAR;
.LBB0_228:
	s_waitcnt lgkmcnt(0)
	v_mov_b32_e32 v14, v230
	s_waitcnt lgkmcnt(0)
	s_barrier
	s_cmp_ge_i32 s2, s88
	s_nop 0
	v_readfirstlane_b32 s8, v14
	s_cbranch_scc1 .LBB0_244
	v_lshlrev_b32_e32 v0, 4, v14
	v_add_u32_e32 v1, 0x2000, v0
	v_ashrrev_i32_e32 v2, 31, v1
	v_lshrrev_b32_e32 v2, 22, v2
	v_add_u32_e32 v2, v1, v2
	v_ashrrev_i32_e32 v8, 10, v2
	v_mul_i32_i24_e32 v2, 0x400, v8
	v_sub_u32_e32 v1, v1, v2
	s_ashr_i32 s9, s8, 6
	v_lshrrev_b32_e32 v2, 4, v1
	s_ashr_i32 s10, s8, 8
	s_lshl_b32 s34, s9, 10
	v_bitop3_b32 v1, v2, v1, 32 bitop3:0x6c
	s_and_b64 s[4:5], s[64:65], exec
	v_ashrrev_i32_e32 v2, 31, v1
	s_mov_b32 s5, 0x8400000
	v_lshrrev_b32_e32 v2, 26, v2
	s_mov_b32 s4, 0x600000
	s_cselect_b32 s5, s5, 0x9400000
	v_add_u32_e32 v2, v1, v2
	v_lshlrev_b32_e32 v3, 3, v8
	s_cselect_b32 s4, s4, 0x280000
	s_add_u32 s5, s78, s5
	v_ashrrev_i32_e32 v9, 6, v2
	v_and_b32_e32 v3, -16, v3
	s_addc_u32 s11, s79, 0
	s_mul_hi_i32 s13, s4, s98
	s_mul_i32 s4, s4, s98
	v_add_u32_e32 v3, v9, v3
	s_add_u32 s35, s5, s4
	v_and_b32_e32 v4, 3, v9
	s_mov_b32 s4, 0x1fffe0
	v_lshrrev_b32_e32 v5, 2, v3
	v_lshlrev_b32_e32 v6, 1, v3
	v_and_b32_e32 v2, 0xc0, v2
	v_and_or_b32 v4, v3, s4, v4
	v_and_b32_e32 v5, 4, v5
	v_and_b32_e32 v6, 24, v6
	v_sub_u32_e32 v1, v1, v2
	v_or3_b32 v4, v4, v5, v6
	v_lshlrev_b32_e32 v5, 5, v8
	v_ashrrev_i16_sdwa v1, v233, sext(v1) dst_sel:DWORD dst_unused:UNUSED_PAD src0_sel:DWORD src1_sel:BYTE_0
	v_and_b32_e32 v5, 32, v5
	v_bfe_i32 v10, v1, 0, 16
	v_add_lshl_u32 v1, v5, v10, 1
	v_lshl_add_u32 v128, v4, 11, v1
	v_lshl_add_u32 v130, v3, 11, v1
	v_bfe_i32 v1, v14, 27, 1
	v_lshrrev_b32_e32 v1, 22, v1
	v_add_u32_e32 v1, v0, v1
	v_and_b32_e32 v1, 0xfffffc00, v1
	v_sub_u32_e32 v0, v0, v1
	v_lshrrev_b32_e32 v1, 4, v0
	v_ashrrev_i32_e32 v2, 31, v14
	v_bitop3_b32 v0, v1, v0, 32 bitop3:0x6c
	v_lshrrev_b32_e32 v2, 26, v2
	v_ashrrev_i32_e32 v1, 31, v0
	v_add_u32_e32 v2, v14, v2
	v_lshrrev_b32_e32 v1, 26, v1
	v_ashrrev_i32_e32 v12, 6, v2
	v_add_u32_e32 v1, v0, v1
	v_lshlrev_b32_e32 v2, 3, v12
	v_ashrrev_i32_e32 v11, 6, v1
	v_and_b32_e32 v2, -16, v2
	v_add_u32_e32 v2, v11, v2
	v_and_b32_e32 v3, 3, v11
	v_and_or_b32 v3, v2, s4, v3
	v_readlane_b32 s4, v253, 63
	s_addc_u32 s48, s11, s13
	v_readlane_b32 s5, v254, 0
	s_and_b64 s[4:5], s[4:5], exec
	s_cselect_b32 s4, s27, s21
	v_readlane_b32 s5, v254, 1
	s_mul_i32 s4, s4, s5
	v_readlane_b32 s5, v254, 2
	s_add_i32 s4, s4, s5
	s_abs_i32 s11, s4
	s_mul_hi_u32 s13, s11, s28
	s_mul_i32 s14, s13, s20
	s_sub_i32 s11, s11, s14
	s_ashr_i32 s5, s4, 31
	s_add_i32 s14, s13, 1
	s_sub_i32 s15, s11, s20
	s_cmp_ge_u32 s11, s20
	s_cselect_b32 s13, s14, s13
	s_cselect_b32 s11, s15, s11
	s_add_i32 s14, s13, 1
	s_cmp_ge_u32 s11, s20
	s_cselect_b32 s11, s14, s13
	s_xor_b32 s11, s11, s5
	s_sub_i32 s5, s11, s5
	s_lshl_b32 s11, s5, 3
	v_and_b32_e32 v1, 0xc0, v1
	s_sub_i32 s13, 0x80, s11
	v_sub_u32_e32 v0, v0, v1
	s_min_i32 s13, s13, 8
	v_ashrrev_i16_sdwa v0, v233, sext(v0) dst_sel:DWORD dst_unused:UNUSED_PAD src0_sel:DWORD src1_sel:BYTE_0
	s_abs_i32 s14, s13
	v_bfe_i32 v13, v0, 0, 16
	v_cvt_f32_u32_e32 v0, s14
	s_sub_i32 s16, 0, s14
	s_mul_i32 s5, s5, s20
	s_sub_i32 s4, s4, s5
	v_rcp_iflag_f32_e32 v0, v0
	s_abs_i32 s15, s4
	s_xor_b32 s5, s4, s13
	s_ashr_i32 s5, s5, 31
	v_mul_f32_e32 v0, 0x4f7ffffe, v0
	v_cvt_u32_f32_e32 v0, v0
	v_lshrrev_b32_e32 v4, 2, v2
	v_lshlrev_b32_e32 v5, 1, v2
	v_and_b32_e32 v4, 4, v4
	v_readfirstlane_b32 s17, v0
	s_mul_i32 s16, s16, s17
	s_mul_hi_u32 s16, s17, s16
	s_add_i32 s17, s17, s16
	s_mul_hi_u32 s16, s15, s17
	s_mul_i32 s17, s16, s14
	s_sub_i32 s15, s15, s17
	s_add_i32 s17, s16, 1
	s_sub_i32 s18, s15, s14
	s_cmp_ge_u32 s15, s14
	s_cselect_b32 s16, s17, s16
	s_cselect_b32 s15, s18, s15
	s_add_i32 s17, s16, 1
	s_cmp_ge_u32 s15, s14
	s_cselect_b32 s14, s17, s16
	s_xor_b32 s14, s14, s5
	s_sub_i32 s40, s14, s5
	s_mul_i32 s5, s40, s13
	s_sub_i32 s4, s4, s5
	s_add_i32 s18, s4, s11
	v_and_b32_e32 v5, 24, v5
	s_ashr_i32 s19, s18, 31
	s_ashr_i32 s41, s40, 31
	v_or3_b32 v3, v3, v4, v5
	v_lshlrev_b32_e32 v4, 5, v12
	s_lshl_b64 s[4:5], s[18:19], 19
	s_lshl_b64 s[14:15], s[40:41], 19
	v_and_b32_e32 v4, 32, v4
	s_add_u32 s44, s35, s14
	v_add_lshl_u32 v1, v4, v13, 1
	s_addc_u32 s45, s48, s15
	s_add_i32 s49, s34, 0
	v_lshl_add_u32 v132, v3, 11, v1
	s_add_i32 m0, s49, 0x10000
	v_lshl_add_u32 v134, v2, 11, v1
	global_load_lds_dwordx4 v132, s[44:45]
	s_add_i32 m0, s49, 0x12000
	s_add_u32 s14, s44, 0x40000
	global_load_lds_dwordx4 v128, s[44:45]
	s_addc_u32 s15, s45, 0
	s_add_i32 m0, s49, 0x14000
	v_mov_b32_e32 v133, v157
	global_load_lds_dwordx4 v132, s[14:15]
	s_add_i32 m0, s49, 0x16000
	s_add_u32 s42, s0, s4
	s_addc_u32 s43, s1, s5
	s_add_i32 s50, s49, 0x2000
	global_load_lds_dwordx4 v128, s[14:15]
	s_mov_b32 m0, s49
	s_add_u32 s4, s42, 0x40000
	global_load_lds_dwordx4 v134, s[42:43]
	s_mov_b32 m0, s50
	s_addc_u32 s5, s43, 0
	s_add_i32 s51, s49, 0x4000
	global_load_lds_dwordx4 v130, s[42:43]
	s_mov_b32 m0, s51
	s_add_i32 s52, s49, 0x6000
	global_load_lds_dwordx4 v134, s[4:5]
	s_mov_b32 m0, s52
	v_mov_b32_e32 v129, v157
	global_load_lds_dwordx4 v130, s[4:5]
	v_mov_b32_e32 v135, v157
	v_mov_b32_e32 v131, v157
	s_cmp_eq_u32 s10, 1
	s_mov_b64 s[94:95], s[64:65]
	v_lshl_add_u64 v[6:7], s[44:45], 0, v[132:133]
	v_lshl_add_u64 v[4:5], s[44:45], 0, v[128:129]
	v_lshl_add_u64 v[0:1], s[42:43], 0, v[134:135]
	s_cselect_b64 s[4:5], -1, 0
	s_cmp_lg_u32 s10, 1
	v_lshl_add_u64 v[2:3], s[42:43], 0, v[130:131]
	s_cbranch_scc1 .LBB0_231
	s_setprio 1
	s_barrier

; #define PG8_WAIT_V(n) asm volatile("s_waitcnt vmcnt(" #n ")" ::: "memory")
; #define PG8_BAR __builtin_amdgcn_s_barrier()
; template <class Epi, class Sched, bool ALIGN_EPI = false, bool SP2 = false>
; __device__ __forceinline__ void gemm_phase(PG8_LAS unsigned char* lds, const Gemm g, const Sched& S, const Epi& E) {
;     ...
;     PG8_WAIT_V(0);
;     if constexpr (!ALIGN_EPI) { if (wr == 0) PG8_BAR; }
;     PG8_BAR;
.LBB0_243:
	s_waitcnt vmcnt(0)
	v_readlane_b32 s58, v254, 33
	v_readlane_b32 s59, v254, 34
	s_mov_b64 s[64:65], s[94:95]
	s_setprio 0
	s_barrier

; #define PG8_STAGE(bufoff, gbase, voff) do { _Pragma("unroll") for (int _i = 0; _i < 2; ++_i) \
;         __builtin_amdgcn_global_load_lds((const unsigned*)((const char*)(gbase) + (voff)[_i]), (PG8_LAS unsigned*)(lds + (bufoff) + ldsw + _i * 8192), 16, 0, 0); } while (0)
; #define PG8_BAR __builtin_amdgcn_s_barrier()
; template <class Epi, class Sched, bool ALIGN_EPI = false, bool SP2 = false>
; __device__ __forceinline__ void gemm_phase(PG8_LAS unsigned char* lds, const Gemm g, const Sched& S, const Epi& E) {
;     ...
;     const int tid = tid_, wid = __builtin_amdgcn_readfirstlane(tid >> 6), lane = tid & 63, wr = wid >> 2, wc = wid & 3, fr = lane & 15, fq = lane >> 4;
;     const int K = g.K, nt = K / BK;
;     unsigned voffA[2], voffB[2];
; #pragma unroll
;     for (int i = 0; i < 2; ++i) { int R, C; stage_rc(tid * 16 + i * 8192, R, C); const int Rb = Epi::PERM ? ((R & ~31) + perm32(R & 31)) : R;
;         voffA[i] = (unsigned)(R * K + C) * 2u; voffB[i] = (unsigned)(Rb * K + C) * 2u; }
;     ...
;     const char* cA = (const char*)g.A + (size_t)cur.pm * tstep; const char* cB = (const char*)g.Bt + (size_t)cur.pn * tstep;
;     S.a_ready(cur);
;     if constexpr (SP2) {
;         PG8_STAGE(PG8_SB(0, 0), cB, voffB); PG8_STAGE(PG8_SB(0, 1), cB + hstep, voffB); PG8_STAGE(PG8_SA(0, 0), cA, voffA); PG8_STAGE(PG8_SA(0, 1), cA + hstep, voffA);
;         if (wr == 1) PG8_BAR;
.LBB0_246:
	s_and_b64 vcc, exec, s[4:5]
	v_cmp_ne_u32_e64 s[38:39], 1, v231
	s_cbranch_vccz .LBB0_340
	s_waitcnt lgkmcnt(0)
	v_mov_b32_e32 v12, v230
	s_and_b64 vcc, exec, s[38:39]
	v_readfirstlane_b32 s6, v12
	s_cbranch_vccnz .LBB0_339
	s_cmp_lg_u32 s26, 1
	s_cselect_b64 s[4:5], -1, 0
	v_cndmask_b32_e64 v0, 0, 1, s[4:5]
	s_lshl_b32 s4, s25, 1
	v_readfirstlane_b32 s5, v0
	v_lshlrev_b32_e32 v0, 4, v12
	v_add_u32_e32 v1, 0x2000, v0
	v_ashrrev_i32_e32 v2, 31, v1
	v_lshrrev_b32_e32 v2, 22, v2
	v_add_u32_e32 v2, v1, v2
	v_ashrrev_i32_e32 v4, 10, v2
	v_mul_i32_i24_e32 v2, 0x400, v4
	v_sub_u32_e32 v1, v1, v2
	v_lshrrev_b32_e32 v2, 4, v1
	v_bitop3_b32 v1, v2, v1, 32 bitop3:0x6c
	v_ashrrev_i32_e32 v2, 31, v1
	v_lshrrev_b32_e32 v2, 26, v2
	s_or_b32 s4, s4, s5
	v_add_u32_e32 v2, v1, v2
	v_lshlrev_b32_e32 v3, 3, v4
	s_mul_hi_i32 s5, s4, 0x580000
	s_mul_i32 s4, s4, 0x580000
	v_ashrrev_i32_e32 v5, 6, v2
	v_and_b32_e32 v3, -16, v3
	s_add_u32 s18, s70, s4
	v_add_u32_e32 v3, v5, v3
	s_addc_u32 s19, s71, s5
	v_and_b32_e32 v6, 3, v5
	s_mov_b32 s5, 0xffffe0
	v_lshrrev_b32_e32 v7, 2, v3
	v_lshlrev_b32_e32 v8, 1, v3
	v_and_or_b32 v6, v3, s5, v6
	v_and_b32_e32 v7, 4, v7
	v_and_b32_e32 v8, 24, v8
	v_and_b32_e32 v2, 0xc0, v2
	v_or3_b32 v6, v6, v7, v8
	v_sub_u32_e32 v1, v1, v2
	v_mul_u32_u24_e32 v8, 0xb00, v6
	v_lshlrev_b32_e32 v6, 5, v4
	v_ashrrev_i16_sdwa v1, v233, sext(v1) dst_sel:DWORD dst_unused:UNUSED_PAD src0_sel:DWORD src1_sel:BYTE_0
	v_and_b32_e32 v6, 32, v6
	v_bfe_i32 v7, v1, 0, 16
	s_movk_i32 s4, 0xb00
	v_add_u32_e32 v1, v6, v7
	v_mul_lo_u32 v2, v3, s4
	v_add_lshl_u32 v170, v8, v1, 1
	v_add_lshl_u32 v172, v1, v2, 1
	v_bfe_i32 v1, v12, 27, 1
	v_lshrrev_b32_e32 v1, 22, v1
	v_add_u32_e32 v1, v0, v1
	v_and_b32_e32 v1, 0xfffffc00, v1
	v_sub_u32_e32 v0, v0, v1
	v_lshrrev_b32_e32 v1, 4, v0
	v_ashrrev_i32_e32 v2, 31, v12
	v_bitop3_b32 v0, v1, v0, 32 bitop3:0x6c
	v_lshrrev_b32_e32 v2, 26, v2
	v_ashrrev_i32_e32 v1, 31, v0
	v_add_u32_e32 v2, v12, v2
	v_lshrrev_b32_e32 v1, 26, v1
	v_ashrrev_i32_e32 v9, 6, v2
	v_add_u32_e32 v1, v0, v1
	v_lshlrev_b32_e32 v2, 3, v9
	v_ashrrev_i32_e32 v8, 6, v1
	v_and_b32_e32 v2, -16, v2
	v_add_u32_e32 v2, v8, v2
	v_and_b32_e32 v3, 3, v8
	v_lshrrev_b32_e32 v10, 2, v2
	v_lshlrev_b32_e32 v11, 1, v2
	v_and_b32_e32 v1, 0xc0, v1
	s_ashr_i32 s8, s6, 6
	v_and_or_b32 v3, v2, s5, v3
	v_and_b32_e32 v10, 4, v10
	v_and_b32_e32 v11, 24, v11
	v_sub_u32_e32 v0, v0, v1
	v_readlane_b32 s5, v254, 6
	s_ashr_i32 s7, s6, 8
	s_lshl_b32 s20, s8, 10
	v_or3_b32 v3, v3, v10, v11
	v_lshlrev_b32_e32 v10, 5, v9
	v_ashrrev_i16_sdwa v0, v233, sext(v0) dst_sel:DWORD dst_unused:UNUSED_PAD src0_sel:DWORD src1_sel:BYTE_0
	v_mul_lo_u32 v1, v2, s4
	s_mul_i32 s4, s5, 0x160000
	v_and_b32_e32 v10, 32, v10
	v_bfe_i32 v11, v0, 0, 16
	s_add_u32 s12, s18, s4
	s_mul_hi_i32 s4, s5, 0x160000
	v_mul_u32_u24_e32 v3, 0xb00, v3
	v_add_u32_e32 v0, v10, v11
	s_addc_u32 s13, s19, s4
	s_add_i32 s21, s20, 0
	v_add_lshl_u32 v156, v3, v0, 1
	s_add_i32 m0, s21, 0x10000
	v_add_lshl_u32 v174, v0, v1, 1
	global_load_lds_dwordx4 v156, s[12:13]
	s_add_i32 m0, s21, 0x12000
	s_add_u32 s4, s12, 0xb0000
	global_load_lds_dwordx4 v170, s[12:13]
	s_addc_u32 s5, s13, 0
	s_add_i32 m0, s21, 0x14000
	s_add_i32 s27, s21, 0x2000
	global_load_lds_dwordx4 v156, s[4:5]
	s_add_i32 m0, s21, 0x16000
	s_add_i32 s54, s21, 0x4000
	global_load_lds_dwordx4 v170, s[4:5]
	v_readlane_b32 s4, v254, 23
	s_mov_b32 m0, s21
	v_readlane_b32 s5, v254, 24
	s_add_i32 s55, s21, 0x6000
	v_mov_b32_e32 v171, v157
	s_cmp_eq_u32 s7, 1
	v_lshl_add_u64 v[0:1], s[12:13], 0, v[156:157]
	v_lshl_add_u64 v[2:3], s[12:13], 0, v[170:171]
	global_load_lds_dwordx4 v174, s[4:5]
	s_mov_b32 m0, s27
	s_nop 0
	global_load_lds_dwordx4 v172, s[4:5]
	v_readlane_b32 s4, v254, 25
	s_mov_b32 m0, s54
	v_readlane_b32 s5, v254, 26
	s_nop 4
	global_load_lds_dwordx4 v174, s[4:5]
	s_mov_b32 m0, s55
	s_nop 0
	global_load_lds_dwordx4 v172, s[4:5]
	s_cselect_b64 s[4:5], -1, 0
	s_cmp_lg_u32 s7, 1
	s_cbranch_scc1 .LBB0_250
	s_setprio 1
	s_barrier

; #define PG8_WAIT_V(n) asm volatile("s_waitcnt vmcnt(" #n ")" ::: "memory")
; #define PG8_BAR __builtin_amdgcn_s_barrier()
; template <class Epi, class Sched, bool ALIGN_EPI = false, bool SP2 = false>
; __device__ __forceinline__ void gemm_phase(PG8_LAS unsigned char* lds, const Gemm g, const Sched& S, const Epi& E) {
;     ...
;     PG8_WAIT_V(0);
;     if constexpr (!ALIGN_EPI) { if (wr == 0) PG8_BAR; }
;     PG8_BAR;
.LBB0_338:
	s_waitcnt vmcnt(0)
	v_readlane_b32 s58, v254, 33
	v_readlane_b32 s28, v254, 35
	v_readlane_b32 s20, v254, 37
	v_readlane_b32 s59, v254, 34
	v_readlane_b32 s29, v254, 36
	v_readlane_b32 s21, v254, 38
	s_setprio 0
	s_barrier

; #define PG8_STAGE(bufoff, gbase, voff) do { _Pragma("unroll") for (int _i = 0; _i < 2; ++_i) \
;         __builtin_amdgcn_global_load_lds((const unsigned*)((const char*)(gbase) + (voff)[_i]), (PG8_LAS unsigned*)(lds + (bufoff) + ldsw + _i * 8192), 16, 0, 0); } while (0)
; #define PG8_BAR __builtin_amdgcn_s_barrier()
; template <class Epi, class Sched, bool ALIGN_EPI = false, bool SP2 = false>
; __device__ __forceinline__ void gemm_phase(PG8_LAS unsigned char* lds, const Gemm g, const Sched& S, const Epi& E) {
;     ...
;     const int tid = tid_, wid = __builtin_amdgcn_readfirstlane(tid >> 6), lane = tid & 63, wr = wid >> 2, wc = wid & 3, fr = lane & 15, fq = lane >> 4;
;     const int K = g.K, nt = K / BK;
;     unsigned voffA[2], voffB[2];
; #pragma unroll
;     for (int i = 0; i < 2; ++i) { int R, C; stage_rc(tid * 16 + i * 8192, R, C); const int Rb = Epi::PERM ? ((R & ~31) + perm32(R & 31)) : R;
;         voffA[i] = (unsigned)(R * K + C) * 2u; voffB[i] = (unsigned)(Rb * K + C) * 2u; }
;     ...
;     const char* cA = (const char*)g.A + (size_t)cur.pm * tstep; const char* cB = (const char*)g.Bt + (size_t)cur.pn * tstep;
;     S.a_ready(cur);
;     if constexpr (SP2) {
;         PG8_STAGE(PG8_SB(0, 0), cB, voffB); PG8_STAGE(PG8_SB(0, 1), cB + hstep, voffB); PG8_STAGE(PG8_SA(0, 0), cA, voffA); PG8_STAGE(PG8_SA(0, 1), cA + hstep, voffA);
;         if (wr == 1) PG8_BAR;
.LBB0_342:
	v_readlane_b32 s94, v254, 57
	s_andn2_b64 vcc, exec, s[6:7]
	v_readlane_b32 s95, v254, 58
	s_cbranch_vccnz .LBB0_366
	v_mov_b32_e32 v10, v230
	s_and_b64 vcc, exec, s[38:39]
	v_readfirstlane_b32 s6, v10
	s_cbranch_vccnz .LBB0_365
	v_lshlrev_b32_e32 v0, 4, v10
	v_add_u32_e32 v1, 0x2000, v0
	v_ashrrev_i32_e32 v2, 31, v1
	v_lshrrev_b32_e32 v2, 22, v2
	v_add_u32_e32 v2, v1, v2
	v_ashrrev_i32_e32 v4, 10, v2
	v_mul_i32_i24_e32 v2, 0x400, v4
	v_sub_u32_e32 v1, v1, v2
	v_lshrrev_b32_e32 v2, 4, v1
	s_ashr_i32 s99, s98, 31
	v_bitop3_b32 v1, v2, v1, 32 bitop3:0x6c
	s_lshl_b64 s[4:5], s[98:99], 21
	v_ashrrev_i32_e32 v2, 31, v1
	s_and_b64 s[8:9], s[64:65], exec
	s_mov_b32 s7, 0x9000000
	v_lshrrev_b32_e32 v2, 26, v2
	s_cselect_b32 s7, s7, 0x9900000
	v_add_u32_e32 v2, v1, v2
	v_lshlrev_b32_e32 v3, 3, v4
	s_add_u32 s7, s78, s7
	s_waitcnt lgkmcnt(0)
	v_ashrrev_i32_e32 v5, 6, v2
	v_and_b32_e32 v3, -16, v3
	s_addc_u32 s8, s79, 0
	v_add_u32_e32 v3, v5, v3
	s_add_u32 s12, s7, s4
	v_and_b32_e32 v6, 3, v5
	s_mov_b32 s4, 0x1fffe0
	v_lshrrev_b32_e32 v7, 2, v3
	v_lshlrev_b32_e32 v8, 1, v3
	v_and_b32_e32 v2, 0xc0, v2
	v_and_or_b32 v6, v3, s4, v6
	v_and_b32_e32 v7, 4, v7
	v_and_b32_e32 v8, 24, v8
	v_sub_u32_e32 v1, v1, v2
	v_or3_b32 v7, v6, v7, v8
	v_lshlrev_b32_e32 v6, 5, v4
	v_ashrrev_i16_sdwa v1, v233, sext(v1) dst_sel:DWORD dst_unused:UNUSED_PAD src0_sel:DWORD src1_sel:BYTE_0
	v_and_b32_e32 v8, 32, v6
	v_bfe_i32 v6, v1, 0, 16
	v_add_lshl_u32 v1, v8, v6, 1
	v_lshl_add_u32 v170, v7, 11, v1
	v_lshl_add_u32 v172, v3, 11, v1
	v_bfe_i32 v1, v10, 27, 1
	v_lshrrev_b32_e32 v1, 22, v1
	v_add_u32_e32 v1, v0, v1
	v_and_b32_e32 v1, 0xfffffc00, v1
	v_sub_u32_e32 v0, v0, v1
	v_lshrrev_b32_e32 v1, 4, v0
	v_ashrrev_i32_e32 v2, 31, v10
	v_bitop3_b32 v0, v1, v0, 32 bitop3:0x6c
	v_lshrrev_b32_e32 v2, 26, v2
	v_ashrrev_i32_e32 v1, 31, v0
	v_add_u32_e32 v2, v10, v2
	v_lshrrev_b32_e32 v1, 26, v1
	v_ashrrev_i32_e32 v8, 6, v2
	v_add_u32_e32 v1, v0, v1
	v_lshlrev_b32_e32 v2, 3, v8
	v_ashrrev_i32_e32 v7, 6, v1
	v_and_b32_e32 v2, -16, v2
	v_add_u32_e32 v2, v7, v2
	v_and_b32_e32 v3, 3, v7
	v_lshrrev_b32_e32 v9, 2, v2
	v_lshlrev_b32_e32 v11, 1, v2
	v_and_b32_e32 v1, 0xc0, v1
	s_addc_u32 s13, s8, s5
	s_ashr_i32 s10, s6, 6
	v_and_or_b32 v3, v2, s4, v3
	v_and_b32_e32 v9, 4, v9
	v_and_b32_e32 v11, 24, v11
	v_sub_u32_e32 v0, v0, v1
	s_ashr_i32 s7, s6, 8
	s_lshl_b32 s14, s10, 10
	v_or3_b32 v3, v3, v9, v11
	v_lshlrev_b32_e32 v9, 5, v8
	v_ashrrev_i16_sdwa v0, v233, sext(v0) dst_sel:DWORD dst_unused:UNUSED_PAD src0_sel:DWORD src1_sel:BYTE_0
	v_readlane_b32 s4, v254, 13
	v_and_b32_e32 v11, 32, v9
	v_bfe_i32 v9, v0, 0, 16
	v_readlane_b32 s5, v254, 14
	s_add_u32 s8, s12, s4
	v_add_lshl_u32 v0, v11, v9, 1
	s_addc_u32 s9, s13, s5
	s_add_i32 s15, s14, 0
	v_lshl_add_u32 v156, v3, 11, v0
	s_add_i32 m0, s15, 0x10000
	v_lshl_add_u32 v174, v2, 11, v0
	global_load_lds_dwordx4 v156, s[8:9]
	s_add_i32 m0, s15, 0x12000
	s_add_u32 s4, s8, 0x40000
	global_load_lds_dwordx4 v170, s[8:9]
	s_addc_u32 s5, s9, 0
	s_add_i32 m0, s15, 0x14000
	s_add_i32 s16, s15, 0x2000
	global_load_lds_dwordx4 v156, s[4:5]
	s_add_i32 m0, s15, 0x16000
	s_add_i32 s17, s15, 0x4000
	global_load_lds_dwordx4 v170, s[4:5]
	v_readlane_b32 s4, v254, 17
	s_mov_b32 m0, s15
	v_readlane_b32 s5, v254, 18
	s_add_i32 s18, s15, 0x6000
	v_mov_b32_e32 v171, v157
	s_cmp_eq_u32 s7, 1
	v_lshl_add_u64 v[0:1], s[8:9], 0, v[156:157]
	v_lshl_add_u64 v[2:3], s[8:9], 0, v[170:171]
	global_load_lds_dwordx4 v174, s[4:5]
	s_mov_b32 m0, s16
	s_nop 0
	global_load_lds_dwordx4 v172, s[4:5]
	v_readlane_b32 s4, v254, 19
	s_mov_b32 m0, s17
	v_readlane_b32 s5, v254, 20
	s_nop 4
	global_load_lds_dwordx4 v174, s[4:5]
	s_mov_b32 m0, s18
	s_nop 0
	global_load_lds_dwordx4 v172, s[4:5]
	s_cselect_b64 s[4:5], -1, 0
	s_cmp_lg_u32 s7, 1
	s_cbranch_scc1 .LBB0_346
	s_setprio 1
	s_barrier

; #define PG8_WAIT_V(n) asm volatile("s_waitcnt vmcnt(" #n ")" ::: "memory")
; #define PG8_BAR __builtin_amdgcn_s_barrier()
; template <class Epi, class Sched, bool ALIGN_EPI = false, bool SP2 = false>
; __device__ __forceinline__ void gemm_phase(PG8_LAS unsigned char* lds, const Gemm g, const Sched& S, const Epi& E) {
;     ...
;     PG8_WAIT_V(0);
;     if constexpr (!ALIGN_EPI) { if (wr == 0) PG8_BAR; }
;     PG8_BAR;
.LBB0_364:
	s_waitcnt vmcnt(0)
	v_readlane_b32 s28, v254, 35
	v_readlane_b32 s20, v254, 37
	v_readlane_b32 s29, v254, 36
	v_readlane_b32 s21, v254, 38
	s_setprio 0
	s_barrier

; #define PG8_STAGE(bufoff, gbase, voff) do { _Pragma("unroll") for (int _i = 0; _i < 2; ++_i) \
;         __builtin_amdgcn_global_load_lds((const unsigned*)((const char*)(gbase) + (voff)[_i]), (PG8_LAS unsigned*)(lds + (bufoff) + ldsw + _i * 8192), 16, 0, 0); } while (0)
; #define PG8_BAR __builtin_amdgcn_s_barrier()
; template <class Epi, class Sched, bool ALIGN_EPI = false, bool SP2 = false>
; __device__ __forceinline__ void gemm_phase(PG8_LAS unsigned char* lds, const Gemm g, const Sched& S, const Epi& E) {
;     ...
;     const int tid = tid_, wid = __builtin_amdgcn_readfirstlane(tid >> 6), lane = tid & 63, wr = wid >> 2, wc = wid & 3, fr = lane & 15, fq = lane >> 4;
;     const int K = g.K, nt = K / BK;
;     unsigned voffA[2], voffB[2];
; #pragma unroll
;     for (int i = 0; i < 2; ++i) { int R, C; stage_rc(tid * 16 + i * 8192, R, C); const int Rb = Epi::PERM ? ((R & ~31) + perm32(R & 31)) : R;
;         voffA[i] = (unsigned)(R * K + C) * 2u; voffB[i] = (unsigned)(Rb * K + C) * 2u; }
;     ...
;     const char* cA = (const char*)g.A + (size_t)cur.pm * tstep; const char* cB = (const char*)g.Bt + (size_t)cur.pn * tstep;
;     S.a_ready(cur);
;     if constexpr (SP2) {
;         PG8_STAGE(PG8_SB(0, 0), cB, voffB); PG8_STAGE(PG8_SB(0, 1), cB + hstep, voffB); PG8_STAGE(PG8_SA(0, 0), cA, voffA); PG8_STAGE(PG8_SA(0, 1), cA + hstep, voffA);
;         if (wr == 1) PG8_BAR;
.LBB0_390:
	v_readlane_b32 s4, v253, 9
	v_mov_b32_e32 v4, v230
	v_readlane_b32 s5, v253, 10
	s_waitcnt vmcnt(0) lgkmcnt(0)
	s_barrier
	s_andn2_b64 vcc, exec, s[4:5]
	v_readfirstlane_b32 s6, v4
	s_cbranch_vccnz .LBB0_406
	s_cmp_lg_u32 s26, 0
	s_cselect_b64 s[4:5], -1, 0
	v_cndmask_b32_e64 v0, 0, 1, s[4:5]
	s_lshl_b32 s4, s25, 1
	v_readfirstlane_b32 s5, v0
	v_lshlrev_b32_e32 v0, 4, v4
	v_add_u32_e32 v1, 0x2000, v0
	v_ashrrev_i32_e32 v2, 31, v1
	v_lshrrev_b32_e32 v2, 22, v2
	v_add_u32_e32 v2, v1, v2
	v_ashrrev_i32_e32 v5, 10, v2
	v_mul_i32_i24_e32 v2, 0x400, v5
	v_sub_u32_e32 v1, v1, v2
	v_lshrrev_b32_e32 v2, 4, v1
	v_bitop3_b32 v1, v2, v1, 32 bitop3:0x6c
	v_ashrrev_i32_e32 v2, 31, v1
	v_lshrrev_b32_e32 v2, 26, v2
	v_add_u32_e32 v2, v1, v2
	v_lshlrev_b32_e32 v3, 3, v5
	s_or_b32 s4, s4, s5
	v_ashrrev_i32_e32 v6, 6, v2
	v_and_b32_e32 v3, -16, v3
	s_mul_hi_i32 s5, s4, 0xb00000
	s_mul_i32 s4, s4, 0xb00000
	v_add_u32_e32 v3, v6, v3
	s_add_u32 s19, s78, s4
	v_and_b32_e32 v7, 3, v6
	s_mov_b32 s4, 0x1fffe0
	v_lshrrev_b32_e32 v8, 2, v3
	v_lshlrev_b32_e32 v9, 1, v3
	v_and_b32_e32 v2, 0xc0, v2
	v_and_or_b32 v7, v3, s4, v7
	v_and_b32_e32 v8, 4, v8
	v_and_b32_e32 v9, 24, v9
	v_sub_u32_e32 v1, v1, v2
	v_or3_b32 v8, v7, v8, v9
	v_lshlrev_b32_e32 v7, 5, v5
	v_ashrrev_i16_sdwa v1, v233, sext(v1) dst_sel:DWORD dst_unused:UNUSED_PAD src0_sel:DWORD src1_sel:BYTE_0
	v_and_b32_e32 v9, 32, v7
	v_bfe_i32 v7, v1, 0, 16
	v_add_lshl_u32 v1, v9, v7, 1
	v_lshl_add_u32 v128, v8, 11, v1
	v_lshl_add_u32 v130, v3, 11, v1
	v_bfe_i32 v1, v4, 27, 1
	v_lshrrev_b32_e32 v1, 22, v1
	v_add_u32_e32 v1, v0, v1
	v_and_b32_e32 v1, 0xfffffc00, v1
	v_sub_u32_e32 v0, v0, v1
	v_lshrrev_b32_e32 v1, 4, v0
	v_ashrrev_i32_e32 v2, 31, v4
	v_bitop3_b32 v0, v1, v0, 32 bitop3:0x6c
	v_lshrrev_b32_e32 v2, 26, v2
	v_ashrrev_i32_e32 v1, 31, v0
	v_add_u32_e32 v2, v4, v2
	v_lshrrev_b32_e32 v1, 26, v1
	v_ashrrev_i32_e32 v9, 6, v2
	v_add_u32_e32 v1, v0, v1
	v_lshlrev_b32_e32 v2, 3, v9
	v_ashrrev_i32_e32 v8, 6, v1
	v_and_b32_e32 v2, -16, v2
	v_add_u32_e32 v2, v8, v2
	v_and_b32_e32 v3, 3, v8
	v_lshrrev_b32_e32 v10, 2, v2
	v_lshlrev_b32_e32 v11, 1, v2
	v_and_b32_e32 v1, 0xc0, v1
	s_addc_u32 s20, s79, s5
	s_ashr_i32 s7, s6, 6
	v_and_or_b32 v3, v2, s4, v3
	v_and_b32_e32 v10, 4, v10
	v_and_b32_e32 v11, 24, v11
	v_sub_u32_e32 v0, v0, v1
	s_ashr_i32 s8, s6, 8
	s_lshl_b32 s21, s7, 10
	v_or3_b32 v3, v3, v10, v11
	v_lshlrev_b32_e32 v10, 5, v9
	v_ashrrev_i16_sdwa v0, v233, sext(v0) dst_sel:DWORD dst_unused:UNUSED_PAD src0_sel:DWORD src1_sel:BYTE_0
	v_readlane_b32 s4, v254, 4
	v_and_b32_e32 v11, 32, v10
	v_bfe_i32 v10, v0, 0, 16
	v_readlane_b32 s5, v254, 5
	s_add_u32 s12, s19, s4
	v_add_lshl_u32 v0, v11, v10, 1
	s_addc_u32 s13, s20, s5
	s_add_i32 s25, s21, 0
	v_lshl_add_u32 v156, v3, 11, v0
	s_add_i32 m0, s25, 0x10000
	v_lshl_add_u32 v132, v2, 11, v0
	global_load_lds_dwordx4 v156, s[12:13]
	s_add_i32 m0, s25, 0x12000
	s_add_u32 s4, s12, 0x40000
	global_load_lds_dwordx4 v128, s[12:13]
	s_addc_u32 s5, s13, 0
	s_add_i32 m0, s25, 0x14000
	s_add_i32 s26, s25, 0x2000
	global_load_lds_dwordx4 v156, s[4:5]
	s_add_i32 m0, s25, 0x16000
	s_add_i32 s27, s25, 0x4000
	global_load_lds_dwordx4 v128, s[4:5]
	v_readlane_b32 s4, v254, 9
	s_mov_b32 m0, s25
	v_readlane_b32 s5, v254, 10
	s_add_i32 s28, s25, 0x6000
	v_mov_b32_e32 v129, v157
	s_cmp_eq_u32 s8, 1
	v_lshl_add_u64 v[0:1], s[12:13], 0, v[156:157]
	v_lshl_add_u64 v[2:3], s[12:13], 0, v[128:129]
	global_load_lds_dwordx4 v132, s[4:5]
	s_mov_b32 m0, s26
	s_nop 0
	global_load_lds_dwordx4 v130, s[4:5]
	v_readlane_b32 s4, v254, 11
	s_mov_b32 m0, s27
	v_readlane_b32 s5, v254, 12
	s_nop 4
	global_load_lds_dwordx4 v132, s[4:5]
	s_mov_b32 m0, s28
	s_nop 0
	global_load_lds_dwordx4 v130, s[4:5]
	s_cselect_b64 s[4:5], -1, 0
	s_cmp_lg_u32 s8, 1
	s_cbranch_scc1 .LBB0_393
	s_setprio 1
	s_barrier
